# v10 minus 16 redundant s_waitcnt lgkmcnt(0) at the head of the GEMM MFMA blocks (already waited before the barrier)
# baseline (speedup 1.0000x reference)
.LBB0_97:
	ds_read_b128 v[34:37], v176
	ds_read_b128 v[38:41], v176 offset:1024
	ds_read_b128 v[50:53], v176 offset:2048
	ds_read_b128 v[54:57], v176 offset:3072
	ds_read_b128 v[162:165], v177
	ds_read_b128 v[166:169], v177 offset:1024
	ds_read_b128 v[170:173], v177 offset:2048
	ds_read_b128 v[180:183], v177 offset:3072
	s_add_u32 s52, s50, 0xfff80080
	s_addc_u32 s53, s51, -1
	s_cmp_eq_u32 s56, 28
	s_cselect_b32 s55, s1, s53
	s_cselect_b32 s54, s7, s52
	s_cselect_b32 s53, s27, s45
	s_cselect_b32 s52, s33, s43
	v_lshl_add_u64 v[216:217], s[50:51], 0, v[154:155]
	s_add_i32 m0, s13, 0xc000
	ds_read_b128 v[184:187], v178
	ds_read_b128 v[188:191], v178 offset:1024
	ds_read_b128 v[192:195], v178 offset:2048
	ds_read_b128 v[196:199], v178 offset:3072
	ds_read_b128 v[200:203], v178 offset:4096
	ds_read_b128 v[204:207], v178 offset:5120
	ds_read_b128 v[208:211], v178 offset:6144
	ds_read_b128 v[212:215], v178 offset:7168
	global_load_lds_dwordx4 v[216:217], off
	v_lshl_add_u64 v[216:217], s[50:51], 0, v[156:157]
	s_add_i32 m0, s13, 0xe000
	s_nop 0
	global_load_lds_dwordx4 v[216:217], off
	s_waitcnt vmcnt(8)
	s_waitcnt lgkmcnt(0)
	s_barrier
	s_setprio 1
	v_mfma_f32_16x16x32_bf16 v[142:145], v[34:37], v[184:187], v[142:145]
	v_mfma_f32_16x16x32_bf16 v[138:141], v[50:53], v[184:187], v[138:141]
	v_mfma_f32_16x16x32_bf16 v[126:129], v[34:37], v[192:195], v[126:129]
	v_mfma_f32_16x16x32_bf16 v[122:125], v[50:53], v[192:195], v[122:125]
	v_mfma_f32_16x16x32_bf16 v[110:113], v[34:37], v[200:203], v[110:113]
	v_mfma_f32_16x16x32_bf16 v[106:109], v[50:53], v[200:203], v[106:109]
	v_mfma_f32_16x16x32_bf16 v[94:97], v[34:37], v[208:211], v[94:97]
	v_mfma_f32_16x16x32_bf16 v[90:93], v[50:53], v[208:211], v[90:93]
	v_mfma_f32_16x16x32_bf16 v[142:145], v[38:41], v[188:191], v[142:145]
	v_mfma_f32_16x16x32_bf16 v[138:141], v[54:57], v[188:191], v[138:141]
	v_mfma_f32_16x16x32_bf16 v[126:129], v[38:41], v[196:199], v[126:129]
	v_mfma_f32_16x16x32_bf16 v[122:125], v[54:57], v[196:199], v[122:125]
	v_mfma_f32_16x16x32_bf16 v[110:113], v[38:41], v[204:207], v[110:113]
	v_mfma_f32_16x16x32_bf16 v[106:109], v[54:57], v[204:207], v[106:109]
	v_mfma_f32_16x16x32_bf16 v[94:97], v[38:41], v[212:215], v[94:97]
	v_mfma_f32_16x16x32_bf16 v[90:93], v[54:57], v[212:215], v[90:93]
	s_setprio 0
	s_setprio 1
	v_mfma_f32_16x16x32_bf16 v[134:137], v[162:165], v[184:187], v[134:137]
	v_mfma_f32_16x16x32_bf16 v[130:133], v[170:173], v[184:187], v[130:133]
	v_mfma_f32_16x16x32_bf16 v[118:121], v[162:165], v[192:195], v[118:121]
	v_mfma_f32_16x16x32_bf16 v[114:117], v[170:173], v[192:195], v[114:117]
	v_mfma_f32_16x16x32_bf16 v[102:105], v[162:165], v[200:203], v[102:105]
	v_mfma_f32_16x16x32_bf16 v[98:101], v[170:173], v[200:203], v[98:101]
	v_mfma_f32_16x16x32_bf16 v[86:89], v[162:165], v[208:211], v[86:89]
	v_mfma_f32_16x16x32_bf16 v[82:85], v[170:173], v[208:211], v[82:85]
	v_mfma_f32_16x16x32_bf16 v[134:137], v[166:169], v[188:191], v[134:137]
	v_mfma_f32_16x16x32_bf16 v[130:133], v[180:183], v[188:191], v[130:133]
	v_mfma_f32_16x16x32_bf16 v[118:121], v[166:169], v[196:199], v[118:121]
	v_mfma_f32_16x16x32_bf16 v[114:117], v[180:183], v[196:199], v[114:117]
	v_mfma_f32_16x16x32_bf16 v[102:105], v[166:169], v[204:207], v[102:105]
	v_mfma_f32_16x16x32_bf16 v[98:101], v[180:183], v[204:207], v[98:101]
	v_mfma_f32_16x16x32_bf16 v[86:89], v[166:169], v[212:215], v[86:89]
	v_mfma_f32_16x16x32_bf16 v[82:85], v[180:183], v[212:215], v[82:85]
	s_setprio 0
	s_barrier
	s_add_i32 s57, s22, s12
	v_lshl_add_u64 v[216:217], s[52:53], 0, v[148:149]
	s_mov_b32 m0, s57
	ds_read_b128 v[184:187], v178 offset:16384
	ds_read_b128 v[188:191], v178 offset:17408
	ds_read_b128 v[192:195], v178 offset:18432
	ds_read_b128 v[196:199], v178 offset:19456
	ds_read_b128 v[200:203], v178 offset:20480
	ds_read_b128 v[204:207], v178 offset:21504
	ds_read_b128 v[208:211], v178 offset:22528
	ds_read_b128 v[212:215], v178 offset:23552
	global_load_lds_dwordx4 v[216:217], off
	s_add_i32 m0, s57, 0x2000
	s_add_u32 s58, s52, 0x80000
	v_lshl_add_u64 v[218:219], s[52:53], 0, v[152:153]
	s_addc_u32 s59, s53, 0
	s_add_i32 s57, s23, s12
	global_load_lds_dwordx4 v[218:219], off
	v_lshl_add_u64 v[220:221], s[58:59], 0, v[148:149]
	s_mov_b32 m0, s57
	v_lshl_add_u64 v[222:223], s[54:55], 0, v[150:151]
	global_load_lds_dwordx4 v[220:221], off
	v_lshl_add_u64 v[220:221], s[58:59], 0, v[152:153]
	s_add_i32 m0, s57, 0x2000
	s_nop 0
	global_load_lds_dwordx4 v[220:221], off
	v_lshl_add_u64 v[220:221], s[54:55], 0, v[146:147]
	s_mov_b32 m0, s13
	s_nop 0
	global_load_lds_dwordx4 v[220:221], off
	s_mov_b32 m0, s14
	s_nop 0
	global_load_lds_dwordx4 v[222:223], off
	s_waitcnt vmcnt(8)
	s_waitcnt lgkmcnt(0)
	s_barrier
	s_setprio 1
	v_mfma_f32_16x16x32_bf16 v[78:81], v[34:37], v[184:187], v[78:81]
	v_mfma_f32_16x16x32_bf16 v[74:77], v[50:53], v[184:187], v[74:77]
	v_mfma_f32_16x16x32_bf16 v[62:65], v[34:37], v[192:195], v[62:65]
	v_mfma_f32_16x16x32_bf16 v[58:61], v[50:53], v[192:195], v[58:61]
	v_mfma_f32_16x16x32_bf16 v[30:33], v[34:37], v[200:203], v[30:33]
	v_mfma_f32_16x16x32_bf16 v[26:29], v[50:53], v[200:203], v[26:29]
	v_mfma_f32_16x16x32_bf16 v[14:17], v[34:37], v[208:211], v[14:17]
	v_mfma_f32_16x16x32_bf16 v[10:13], v[50:53], v[208:211], v[10:13]
	v_mfma_f32_16x16x32_bf16 v[78:81], v[38:41], v[188:191], v[78:81]
	v_mfma_f32_16x16x32_bf16 v[74:77], v[54:57], v[188:191], v[74:77]
	v_mfma_f32_16x16x32_bf16 v[62:65], v[38:41], v[196:199], v[62:65]
	v_mfma_f32_16x16x32_bf16 v[58:61], v[54:57], v[196:199], v[58:61]
	v_mfma_f32_16x16x32_bf16 v[30:33], v[38:41], v[204:207], v[30:33]
	v_mfma_f32_16x16x32_bf16 v[26:29], v[54:57], v[204:207], v[26:29]
	v_mfma_f32_16x16x32_bf16 v[14:17], v[38:41], v[212:215], v[14:17]
	v_mfma_f32_16x16x32_bf16 v[10:13], v[54:57], v[212:215], v[10:13]
	s_setprio 0
	s_setprio 1
	v_mfma_f32_16x16x32_bf16 v[46:49], v[162:165], v[192:195], v[46:49]
	v_mfma_f32_16x16x32_bf16 v[42:45], v[170:173], v[192:195], v[42:45]
	v_mfma_f32_16x16x32_bf16 v[22:25], v[162:165], v[200:203], v[22:25]
	v_mfma_f32_16x16x32_bf16 v[18:21], v[170:173], v[200:203], v[18:21]
	v_mfma_f32_16x16x32_bf16 v[6:9], v[162:165], v[208:211], v[6:9]
	v_mfma_f32_16x16x32_bf16 v[2:5], v[170:173], v[208:211], v[2:5]
	v_mfma_f32_16x16x32_bf16 v[34:37], v[162:165], v[184:187], v[70:73]
	v_mfma_f32_16x16x32_bf16 v[38:41], v[170:173], v[184:187], v[66:69]
	v_mfma_f32_16x16x32_bf16 v[46:49], v[166:169], v[196:199], v[46:49]
	v_mfma_f32_16x16x32_bf16 v[42:45], v[180:183], v[196:199], v[42:45]
	v_mfma_f32_16x16x32_bf16 v[22:25], v[166:169], v[204:207], v[22:25]
	v_mfma_f32_16x16x32_bf16 v[18:21], v[180:183], v[204:207], v[18:21]
	v_mfma_f32_16x16x32_bf16 v[6:9], v[166:169], v[212:215], v[6:9]
	v_mfma_f32_16x16x32_bf16 v[2:5], v[180:183], v[212:215], v[2:5]
	v_mfma_f32_16x16x32_bf16 v[34:37], v[166:169], v[188:191], v[34:37]
	v_mfma_f32_16x16x32_bf16 v[38:41], v[180:183], v[188:191], v[38:41]
	s_setprio 0
	s_barrier
	s_add_i32 s57, 0, 0x18000
	s_add_i32 s58, 0, 0x1c000
	v_add_u32_e32 v70, s57, v174
	v_add_u32_e32 v179, s58, v174
	ds_read_b128 v[50:53], v70
	ds_read_b128 v[54:57], v70 offset:1024
	ds_read_b128 v[66:69], v70 offset:2048
	ds_read_b128 v[70:73], v70 offset:3072
	ds_read_b128 v[162:165], v179
	ds_read_b128 v[166:169], v179 offset:1024
	ds_read_b128 v[170:173], v179 offset:2048
	ds_read_b128 v[180:183], v179 offset:3072
	s_add_u32 s54, s54, 0x80000
	s_addc_u32 s55, s55, 0
	s_mov_b32 m0, s15
	v_lshl_add_u64 v[224:225], s[54:55], 0, v[146:147]
	ds_read_b128 v[184:187], v178 offset:32768
	ds_read_b128 v[188:191], v178 offset:33792
	ds_read_b128 v[192:195], v178 offset:34816
	ds_read_b128 v[196:199], v178 offset:35840
	ds_read_b128 v[200:203], v178 offset:36864
	ds_read_b128 v[204:207], v178 offset:37888
	ds_read_b128 v[208:211], v178 offset:38912
	ds_read_b128 v[212:215], v178 offset:39936
	global_load_lds_dwordx4 v[224:225], off
	v_lshl_add_u64 v[224:225], s[54:55], 0, v[150:151]
	s_mov_b32 m0, s16
	s_nop 0
	global_load_lds_dwordx4 v[224:225], off
	s_waitcnt vmcnt(8)
	s_waitcnt lgkmcnt(0)
	s_barrier
	s_setprio 1
	v_mfma_f32_16x16x32_bf16 v[142:145], v[50:53], v[184:187], v[142:145]
	v_mfma_f32_16x16x32_bf16 v[138:141], v[66:69], v[184:187], v[138:141]
	v_mfma_f32_16x16x32_bf16 v[126:129], v[50:53], v[192:195], v[126:129]
	v_mfma_f32_16x16x32_bf16 v[122:125], v[66:69], v[192:195], v[122:125]
	v_mfma_f32_16x16x32_bf16 v[110:113], v[50:53], v[200:203], v[110:113]
	v_mfma_f32_16x16x32_bf16 v[106:109], v[66:69], v[200:203], v[106:109]
	v_mfma_f32_16x16x32_bf16 v[94:97], v[50:53], v[208:211], v[94:97]
	v_mfma_f32_16x16x32_bf16 v[90:93], v[66:69], v[208:211], v[90:93]
	v_mfma_f32_16x16x32_bf16 v[142:145], v[54:57], v[188:191], v[142:145]
	v_mfma_f32_16x16x32_bf16 v[138:141], v[70:73], v[188:191], v[138:141]
	v_mfma_f32_16x16x32_bf16 v[126:129], v[54:57], v[196:199], v[126:129]
	v_mfma_f32_16x16x32_bf16 v[122:125], v[70:73], v[196:199], v[122:125]
	v_mfma_f32_16x16x32_bf16 v[110:113], v[54:57], v[204:207], v[110:113]
	v_mfma_f32_16x16x32_bf16 v[106:109], v[70:73], v[204:207], v[106:109]
	v_mfma_f32_16x16x32_bf16 v[94:97], v[54:57], v[212:215], v[94:97]
	v_mfma_f32_16x16x32_bf16 v[90:93], v[70:73], v[212:215], v[90:93]
	s_setprio 0
	s_setprio 1
	v_mfma_f32_16x16x32_bf16 v[134:137], v[162:165], v[184:187], v[134:137]
	v_mfma_f32_16x16x32_bf16 v[130:133], v[170:173], v[184:187], v[130:133]
	v_mfma_f32_16x16x32_bf16 v[118:121], v[162:165], v[192:195], v[118:121]
	v_mfma_f32_16x16x32_bf16 v[114:117], v[170:173], v[192:195], v[114:117]
	v_mfma_f32_16x16x32_bf16 v[102:105], v[162:165], v[200:203], v[102:105]
	v_mfma_f32_16x16x32_bf16 v[98:101], v[170:173], v[200:203], v[98:101]
	v_mfma_f32_16x16x32_bf16 v[86:89], v[162:165], v[208:211], v[86:89]
	v_mfma_f32_16x16x32_bf16 v[82:85], v[170:173], v[208:211], v[82:85]
	v_mfma_f32_16x16x32_bf16 v[134:137], v[166:169], v[188:191], v[134:137]
	v_mfma_f32_16x16x32_bf16 v[130:133], v[180:183], v[188:191], v[130:133]
	v_mfma_f32_16x16x32_bf16 v[118:121], v[166:169], v[196:199], v[118:121]
	v_mfma_f32_16x16x32_bf16 v[114:117], v[180:183], v[196:199], v[114:117]
	v_mfma_f32_16x16x32_bf16 v[102:105], v[166:169], v[204:207], v[102:105]
	v_mfma_f32_16x16x32_bf16 v[98:101], v[180:183], v[204:207], v[98:101]
	v_mfma_f32_16x16x32_bf16 v[86:89], v[166:169], v[212:215], v[86:89]
	v_mfma_f32_16x16x32_bf16 v[82:85], v[180:183], v[212:215], v[82:85]
	s_setprio 0
	s_barrier
	s_add_i32 s54, s57, s12
	v_lshl_add_u64 v[216:217], v[216:217], 0, s[30:31]
	s_mov_b32 m0, s54
	ds_read_b128 v[184:187], v178 offset:49152
	ds_read_b128 v[188:191], v178 offset:50176
	ds_read_b128 v[192:195], v178 offset:51200
	ds_read_b128 v[196:199], v178 offset:52224
	ds_read_b128 v[200:203], v178 offset:53248
	ds_read_b128 v[204:207], v178 offset:54272
	ds_read_b128 v[208:211], v178 offset:55296
	ds_read_b128 v[212:215], v178 offset:56320
	global_load_lds_dwordx4 v[216:217], off
	s_add_i32 m0, s54, 0x2000
	s_add_u32 s52, s52, 0x80080
	v_lshl_add_u64 v[216:217], v[218:219], 0, s[30:31]
	s_addc_u32 s53, s53, 0
	s_add_i32 s54, s58, s12
	global_load_lds_dwordx4 v[216:217], off
	v_lshl_add_u64 v[216:217], s[52:53], 0, v[148:149]
	s_mov_b32 m0, s54
	s_nop 0
	global_load_lds_dwordx4 v[216:217], off
	v_lshl_add_u64 v[216:217], s[52:53], 0, v[152:153]
	s_add_i32 m0, s54, 0x2000
	s_nop 0
	global_load_lds_dwordx4 v[216:217], off
	v_lshl_add_u64 v[216:217], v[220:221], 0, s[30:31]
	s_mov_b32 m0, s18
	s_nop 0
	global_load_lds_dwordx4 v[216:217], off
	v_lshl_add_u64 v[216:217], v[222:223], 0, s[30:31]
	s_mov_b32 m0, s19
	s_nop 0
	global_load_lds_dwordx4 v[216:217], off
	s_waitcnt vmcnt(8)
	s_waitcnt lgkmcnt(0)
	s_barrier
	s_setprio 1
	v_mfma_f32_16x16x32_bf16 v[78:81], v[50:53], v[184:187], v[78:81]
	v_mfma_f32_16x16x32_bf16 v[74:77], v[66:69], v[184:187], v[74:77]
	v_mfma_f32_16x16x32_bf16 v[62:65], v[50:53], v[192:195], v[62:65]
	v_mfma_f32_16x16x32_bf16 v[58:61], v[66:69], v[192:195], v[58:61]
	v_mfma_f32_16x16x32_bf16 v[30:33], v[50:53], v[200:203], v[30:33]
	v_mfma_f32_16x16x32_bf16 v[26:29], v[66:69], v[200:203], v[26:29]
	v_mfma_f32_16x16x32_bf16 v[14:17], v[50:53], v[208:211], v[14:17]
	v_mfma_f32_16x16x32_bf16 v[10:13], v[66:69], v[208:211], v[10:13]
	v_mfma_f32_16x16x32_bf16 v[78:81], v[54:57], v[188:191], v[78:81]
	v_mfma_f32_16x16x32_bf16 v[74:77], v[70:73], v[188:191], v[74:77]
	v_mfma_f32_16x16x32_bf16 v[62:65], v[54:57], v[196:199], v[62:65]
	v_mfma_f32_16x16x32_bf16 v[58:61], v[70:73], v[196:199], v[58:61]
	v_mfma_f32_16x16x32_bf16 v[30:33], v[54:57], v[204:207], v[30:33]
	v_mfma_f32_16x16x32_bf16 v[26:29], v[70:73], v[204:207], v[26:29]
	v_mfma_f32_16x16x32_bf16 v[14:17], v[54:57], v[212:215], v[14:17]
	v_mfma_f32_16x16x32_bf16 v[10:13], v[70:73], v[212:215], v[10:13]
	s_setprio 0
	s_setprio 1
	v_mfma_f32_16x16x32_bf16 v[34:37], v[162:165], v[184:187], v[34:37]
	v_mfma_f32_16x16x32_bf16 v[70:73], v[166:169], v[188:191], v[34:37]
	v_mfma_f32_16x16x32_bf16 v[34:37], v[170:173], v[184:187], v[38:41]
	v_mfma_f32_16x16x32_bf16 v[66:69], v[180:183], v[188:191], v[34:37]
	v_mfma_f32_16x16x32_bf16 v[34:37], v[162:165], v[192:195], v[46:49]
	v_mfma_f32_16x16x32_bf16 v[46:49], v[166:169], v[196:199], v[34:37]
	v_mfma_f32_16x16x32_bf16 v[34:37], v[170:173], v[192:195], v[42:45]
	v_mfma_f32_16x16x32_bf16 v[22:25], v[162:165], v[200:203], v[22:25]
	v_mfma_f32_16x16x32_bf16 v[18:21], v[170:173], v[200:203], v[18:21]
	v_mfma_f32_16x16x32_bf16 v[6:9], v[162:165], v[208:211], v[6:9]
	v_mfma_f32_16x16x32_bf16 v[2:5], v[170:173], v[208:211], v[2:5]
	v_mfma_f32_16x16x32_bf16 v[42:45], v[180:183], v[196:199], v[34:37]
	v_mfma_f32_16x16x32_bf16 v[22:25], v[166:169], v[204:207], v[22:25]
	v_mfma_f32_16x16x32_bf16 v[18:21], v[180:183], v[204:207], v[18:21]
	v_mfma_f32_16x16x32_bf16 v[6:9], v[166:169], v[212:215], v[6:9]
	v_mfma_f32_16x16x32_bf16 v[2:5], v[180:183], v[212:215], v[2:5]
	s_setprio 0
	s_barrier
	s_add_i32 s56, s56, 2
	s_add_u32 s50, s50, 0x100
	s_addc_u32 s51, s51, 0
	s_add_u32 s43, s43, 0x100
	s_addc_u32 s45, s45, 0
	s_cmp_gt_u32 s56, 29
	s_cbranch_scc0 .LBB0_97
	s_and_b64 vcc, exec, s[34:35]
	s_cbranch_vccz .LBB0_100
	s_barrier

.LBB0_566:
	ds_read_b128 v[146:149], v158
	ds_read_b128 v[162:165], v158 offset:1024
	ds_read_b128 v[166:169], v158 offset:2048
	ds_read_b128 v[170:173], v158 offset:3072
	ds_read_b128 v[176:179], v159
	ds_read_b128 v[180:183], v159 offset:1024
	ds_read_b128 v[184:187], v159 offset:2048
	ds_read_b128 v[188:191], v159 offset:3072
	s_add_u32 s42, s40, 0xfff80080
	s_addc_u32 s43, s41, -1
	s_cmp_eq_u32 s55, s58
	s_cselect_b32 s45, s13, s43
	s_cselect_b32 s44, s37, s42
	s_cselect_b32 s43, s11, s57
	s_cselect_b32 s42, s39, s56
	v_lshl_add_u64 v[150:151], s[40:41], 0, v[138:139]
	s_add_i32 m0, s23, 0xc000
	ds_read_b128 v[192:195], v160
	ds_read_b128 v[196:199], v160 offset:1024
	ds_read_b128 v[200:203], v160 offset:2048
	ds_read_b128 v[204:207], v160 offset:3072
	ds_read_b128 v[208:211], v160 offset:4096
	ds_read_b128 v[212:215], v160 offset:5120
	ds_read_b128 v[216:219], v160 offset:6144
	ds_read_b128 v[220:223], v160 offset:7168
	global_load_lds_dwordx4 v[150:151], off
	v_lshl_add_u64 v[150:151], s[40:41], 0, v[140:141]
	s_add_i32 m0, s23, 0xe000
	s_nop 0
	global_load_lds_dwordx4 v[150:151], off
	s_waitcnt vmcnt(8)
	s_waitcnt lgkmcnt(0)
	s_barrier
	s_setprio 1
	v_mfma_f32_16x16x32_bf16 v[126:129], v[146:149], v[192:195], v[126:129]
	v_mfma_f32_16x16x32_bf16 v[122:125], v[166:169], v[192:195], v[122:125]
	v_mfma_f32_16x16x32_bf16 v[110:113], v[146:149], v[200:203], v[110:113]
	v_mfma_f32_16x16x32_bf16 v[106:109], v[166:169], v[200:203], v[106:109]
	v_mfma_f32_16x16x32_bf16 v[94:97], v[146:149], v[208:211], v[94:97]
	v_mfma_f32_16x16x32_bf16 v[90:93], v[166:169], v[208:211], v[90:93]
	v_mfma_f32_16x16x32_bf16 v[78:81], v[146:149], v[216:219], v[78:81]
	v_mfma_f32_16x16x32_bf16 v[74:77], v[166:169], v[216:219], v[74:77]
	v_mfma_f32_16x16x32_bf16 v[126:129], v[162:165], v[196:199], v[126:129]
	v_mfma_f32_16x16x32_bf16 v[122:125], v[170:173], v[196:199], v[122:125]
	v_mfma_f32_16x16x32_bf16 v[110:113], v[162:165], v[204:207], v[110:113]
	v_mfma_f32_16x16x32_bf16 v[106:109], v[170:173], v[204:207], v[106:109]
	v_mfma_f32_16x16x32_bf16 v[94:97], v[162:165], v[212:215], v[94:97]
	v_mfma_f32_16x16x32_bf16 v[90:93], v[170:173], v[212:215], v[90:93]
	v_mfma_f32_16x16x32_bf16 v[78:81], v[162:165], v[220:223], v[78:81]
	v_mfma_f32_16x16x32_bf16 v[74:77], v[170:173], v[220:223], v[74:77]
	s_setprio 0
	s_setprio 1
	v_mfma_f32_16x16x32_bf16 v[118:121], v[176:179], v[192:195], v[118:121]
	v_mfma_f32_16x16x32_bf16 v[114:117], v[184:187], v[192:195], v[114:117]
	v_mfma_f32_16x16x32_bf16 v[102:105], v[176:179], v[200:203], v[102:105]
	v_mfma_f32_16x16x32_bf16 v[98:101], v[184:187], v[200:203], v[98:101]
	v_mfma_f32_16x16x32_bf16 v[86:89], v[176:179], v[208:211], v[86:89]
	v_mfma_f32_16x16x32_bf16 v[82:85], v[184:187], v[208:211], v[82:85]
	v_mfma_f32_16x16x32_bf16 v[70:73], v[176:179], v[216:219], v[70:73]
	v_mfma_f32_16x16x32_bf16 v[66:69], v[184:187], v[216:219], v[66:69]
	v_mfma_f32_16x16x32_bf16 v[118:121], v[180:183], v[196:199], v[118:121]
	v_mfma_f32_16x16x32_bf16 v[114:117], v[188:191], v[196:199], v[114:117]
	v_mfma_f32_16x16x32_bf16 v[102:105], v[180:183], v[204:207], v[102:105]
	v_mfma_f32_16x16x32_bf16 v[98:101], v[188:191], v[204:207], v[98:101]
	v_mfma_f32_16x16x32_bf16 v[86:89], v[180:183], v[212:215], v[86:89]
	v_mfma_f32_16x16x32_bf16 v[82:85], v[188:191], v[212:215], v[82:85]
	v_mfma_f32_16x16x32_bf16 v[70:73], v[180:183], v[220:223], v[70:73]
	v_mfma_f32_16x16x32_bf16 v[66:69], v[188:191], v[220:223], v[66:69]
	s_setprio 0
	s_barrier
	s_add_i32 s59, s49, s22
	v_lshl_add_u64 v[150:151], s[42:43], 0, v[132:133]
	s_mov_b32 m0, s59
	ds_read_b128 v[192:195], v160 offset:16384
	ds_read_b128 v[196:199], v160 offset:17408
	ds_read_b128 v[200:203], v160 offset:18432
	ds_read_b128 v[204:207], v160 offset:19456
	ds_read_b128 v[208:211], v160 offset:20480
	ds_read_b128 v[212:215], v160 offset:21504
	ds_read_b128 v[216:219], v160 offset:22528
	ds_read_b128 v[220:223], v160 offset:23552
	global_load_lds_dwordx4 v[150:151], off
	s_add_i32 m0, s59, 0x2000
	s_add_u32 s60, s42, 0x80000
	v_lshl_add_u64 v[224:225], s[42:43], 0, v[136:137]
	s_addc_u32 s61, s43, 0
	s_add_i32 s59, s50, s22
	global_load_lds_dwordx4 v[224:225], off
	v_lshl_add_u64 v[226:227], s[60:61], 0, v[132:133]
	s_mov_b32 m0, s59
	v_lshl_add_u64 v[228:229], s[44:45], 0, v[134:135]
	global_load_lds_dwordx4 v[226:227], off
	v_lshl_add_u64 v[226:227], s[60:61], 0, v[136:137]
	s_add_i32 m0, s59, 0x2000
	s_nop 0
	global_load_lds_dwordx4 v[226:227], off
	v_lshl_add_u64 v[226:227], s[44:45], 0, v[130:131]
	s_mov_b32 m0, s23
	s_nop 0
	global_load_lds_dwordx4 v[226:227], off
	s_mov_b32 m0, s24
	s_nop 0
	global_load_lds_dwordx4 v[228:229], off
	s_waitcnt vmcnt(8)
	s_waitcnt lgkmcnt(0)
	s_barrier
	s_setprio 1
	v_mfma_f32_16x16x32_bf16 v[62:65], v[146:149], v[192:195], v[62:65]
	v_mfma_f32_16x16x32_bf16 v[58:61], v[166:169], v[192:195], v[58:61]
	v_mfma_f32_16x16x32_bf16 v[46:49], v[146:149], v[200:203], v[46:49]
	v_mfma_f32_16x16x32_bf16 v[42:45], v[166:169], v[200:203], v[42:45]
	v_mfma_f32_16x16x32_bf16 v[30:33], v[146:149], v[208:211], v[30:33]
	v_mfma_f32_16x16x32_bf16 v[26:29], v[166:169], v[208:211], v[26:29]
	v_mfma_f32_16x16x32_bf16 v[14:17], v[146:149], v[216:219], v[14:17]
	v_mfma_f32_16x16x32_bf16 v[10:13], v[166:169], v[216:219], v[10:13]
	v_mfma_f32_16x16x32_bf16 v[62:65], v[162:165], v[196:199], v[62:65]
	v_mfma_f32_16x16x32_bf16 v[58:61], v[170:173], v[196:199], v[58:61]
	v_mfma_f32_16x16x32_bf16 v[46:49], v[162:165], v[204:207], v[46:49]
	v_mfma_f32_16x16x32_bf16 v[42:45], v[170:173], v[204:207], v[42:45]
	v_mfma_f32_16x16x32_bf16 v[30:33], v[162:165], v[212:215], v[30:33]
	v_mfma_f32_16x16x32_bf16 v[26:29], v[170:173], v[212:215], v[26:29]
	v_mfma_f32_16x16x32_bf16 v[14:17], v[162:165], v[220:223], v[14:17]
	v_mfma_f32_16x16x32_bf16 v[10:13], v[170:173], v[220:223], v[10:13]
	s_setprio 0
	s_setprio 1
	v_mfma_f32_16x16x32_bf16 v[54:57], v[176:179], v[192:195], v[54:57]
	v_mfma_f32_16x16x32_bf16 v[50:53], v[184:187], v[192:195], v[50:53]
	v_mfma_f32_16x16x32_bf16 v[38:41], v[176:179], v[200:203], v[38:41]
	v_mfma_f32_16x16x32_bf16 v[34:37], v[184:187], v[200:203], v[34:37]
	v_mfma_f32_16x16x32_bf16 v[22:25], v[176:179], v[208:211], v[22:25]
	v_mfma_f32_16x16x32_bf16 v[18:21], v[184:187], v[208:211], v[18:21]
	v_mfma_f32_16x16x32_bf16 v[6:9], v[176:179], v[216:219], v[6:9]
	v_mfma_f32_16x16x32_bf16 v[2:5], v[184:187], v[216:219], v[2:5]
	v_mfma_f32_16x16x32_bf16 v[54:57], v[180:183], v[196:199], v[54:57]
	v_mfma_f32_16x16x32_bf16 v[50:53], v[188:191], v[196:199], v[50:53]
	v_mfma_f32_16x16x32_bf16 v[38:41], v[180:183], v[204:207], v[38:41]
	v_mfma_f32_16x16x32_bf16 v[34:37], v[188:191], v[204:207], v[34:37]
	v_mfma_f32_16x16x32_bf16 v[22:25], v[180:183], v[212:215], v[22:25]
	v_mfma_f32_16x16x32_bf16 v[18:21], v[188:191], v[212:215], v[18:21]
	v_mfma_f32_16x16x32_bf16 v[6:9], v[180:183], v[220:223], v[6:9]
	v_mfma_f32_16x16x32_bf16 v[2:5], v[188:191], v[220:223], v[2:5]
	s_setprio 0
	s_barrier
	s_add_i32 s59, 0, 0x18000
	v_add_u32_e32 v161, s59, v152
	s_add_i32 s60, 0, 0x1c000
	ds_read_b128 v[146:149], v161
	ds_read_b128 v[162:165], v161 offset:1024
	ds_read_b128 v[166:169], v161 offset:2048
	ds_read_b128 v[170:173], v161 offset:3072
	v_add_u32_e32 v161, s60, v152
	ds_read_b128 v[176:179], v161
	ds_read_b128 v[180:183], v161 offset:1024
	ds_read_b128 v[184:187], v161 offset:2048
	ds_read_b128 v[188:191], v161 offset:3072
	s_add_u32 s44, s44, 0x80000
	s_addc_u32 s45, s45, 0
	s_mov_b32 m0, s25
	v_lshl_add_u64 v[230:231], s[44:45], 0, v[130:131]
	ds_read_b128 v[192:195], v160 offset:32768
	ds_read_b128 v[196:199], v160 offset:33792
	ds_read_b128 v[200:203], v160 offset:34816
	ds_read_b128 v[204:207], v160 offset:35840
	ds_read_b128 v[208:211], v160 offset:36864
	ds_read_b128 v[212:215], v160 offset:37888
	ds_read_b128 v[216:219], v160 offset:38912
	ds_read_b128 v[220:223], v160 offset:39936
	global_load_lds_dwordx4 v[230:231], off
	v_lshl_add_u64 v[230:231], s[44:45], 0, v[134:135]
	s_mov_b32 m0, s26
	s_nop 0
	global_load_lds_dwordx4 v[230:231], off
	s_waitcnt vmcnt(8)
	s_waitcnt lgkmcnt(0)
	s_barrier
	s_setprio 1
	v_mfma_f32_16x16x32_bf16 v[126:129], v[146:149], v[192:195], v[126:129]
	v_mfma_f32_16x16x32_bf16 v[122:125], v[166:169], v[192:195], v[122:125]
	v_mfma_f32_16x16x32_bf16 v[110:113], v[146:149], v[200:203], v[110:113]
	v_mfma_f32_16x16x32_bf16 v[106:109], v[166:169], v[200:203], v[106:109]
	v_mfma_f32_16x16x32_bf16 v[94:97], v[146:149], v[208:211], v[94:97]
	v_mfma_f32_16x16x32_bf16 v[90:93], v[166:169], v[208:211], v[90:93]
	v_mfma_f32_16x16x32_bf16 v[78:81], v[146:149], v[216:219], v[78:81]
	v_mfma_f32_16x16x32_bf16 v[74:77], v[166:169], v[216:219], v[74:77]
	v_mfma_f32_16x16x32_bf16 v[126:129], v[162:165], v[196:199], v[126:129]
	v_mfma_f32_16x16x32_bf16 v[122:125], v[170:173], v[196:199], v[122:125]
	v_mfma_f32_16x16x32_bf16 v[110:113], v[162:165], v[204:207], v[110:113]
	v_mfma_f32_16x16x32_bf16 v[106:109], v[170:173], v[204:207], v[106:109]
	v_mfma_f32_16x16x32_bf16 v[94:97], v[162:165], v[212:215], v[94:97]
	v_mfma_f32_16x16x32_bf16 v[90:93], v[170:173], v[212:215], v[90:93]
	v_mfma_f32_16x16x32_bf16 v[78:81], v[162:165], v[220:223], v[78:81]
	v_mfma_f32_16x16x32_bf16 v[74:77], v[170:173], v[220:223], v[74:77]
	s_setprio 0
	s_setprio 1
	v_mfma_f32_16x16x32_bf16 v[118:121], v[176:179], v[192:195], v[118:121]
	v_mfma_f32_16x16x32_bf16 v[114:117], v[184:187], v[192:195], v[114:117]
	v_mfma_f32_16x16x32_bf16 v[102:105], v[176:179], v[200:203], v[102:105]
	v_mfma_f32_16x16x32_bf16 v[98:101], v[184:187], v[200:203], v[98:101]
	v_mfma_f32_16x16x32_bf16 v[86:89], v[176:179], v[208:211], v[86:89]
	v_mfma_f32_16x16x32_bf16 v[82:85], v[184:187], v[208:211], v[82:85]
	v_mfma_f32_16x16x32_bf16 v[70:73], v[176:179], v[216:219], v[70:73]
	v_mfma_f32_16x16x32_bf16 v[66:69], v[184:187], v[216:219], v[66:69]
	v_mfma_f32_16x16x32_bf16 v[118:121], v[180:183], v[196:199], v[118:121]
	v_mfma_f32_16x16x32_bf16 v[114:117], v[188:191], v[196:199], v[114:117]
	v_mfma_f32_16x16x32_bf16 v[102:105], v[180:183], v[204:207], v[102:105]
	v_mfma_f32_16x16x32_bf16 v[98:101], v[188:191], v[204:207], v[98:101]
	v_mfma_f32_16x16x32_bf16 v[86:89], v[180:183], v[212:215], v[86:89]
	v_mfma_f32_16x16x32_bf16 v[82:85], v[188:191], v[212:215], v[82:85]
	v_mfma_f32_16x16x32_bf16 v[70:73], v[180:183], v[220:223], v[70:73]
	v_mfma_f32_16x16x32_bf16 v[66:69], v[188:191], v[220:223], v[66:69]
	s_setprio 0
	s_barrier
	s_add_i32 s44, s59, s22
	v_lshl_add_u64 v[150:151], v[150:151], 0, s[2:3]
	s_mov_b32 m0, s44
	ds_read_b128 v[192:195], v160 offset:49152
	ds_read_b128 v[196:199], v160 offset:50176
	ds_read_b128 v[200:203], v160 offset:51200
	ds_read_b128 v[204:207], v160 offset:52224
	ds_read_b128 v[208:211], v160 offset:53248
	ds_read_b128 v[212:215], v160 offset:54272
	ds_read_b128 v[216:219], v160 offset:55296
	ds_read_b128 v[220:223], v160 offset:56320
	global_load_lds_dwordx4 v[150:151], off
	s_add_i32 m0, s44, 0x2000
	s_add_u32 s42, s42, 0x80080
	v_lshl_add_u64 v[150:151], v[224:225], 0, s[2:3]
	s_addc_u32 s43, s43, 0
	s_add_i32 s44, s60, s22
	global_load_lds_dwordx4 v[150:151], off
	v_lshl_add_u64 v[150:151], s[42:43], 0, v[132:133]
	s_mov_b32 m0, s44
	s_nop 0
	global_load_lds_dwordx4 v[150:151], off
	v_lshl_add_u64 v[150:151], s[42:43], 0, v[136:137]
	s_add_i32 m0, s44, 0x2000
	s_nop 0
	global_load_lds_dwordx4 v[150:151], off
	v_lshl_add_u64 v[150:151], v[226:227], 0, s[2:3]
	s_mov_b32 m0, s33
	s_nop 0
	global_load_lds_dwordx4 v[150:151], off
	v_lshl_add_u64 v[150:151], v[228:229], 0, s[2:3]
	s_mov_b32 m0, s46
	s_nop 0
	global_load_lds_dwordx4 v[150:151], off
	s_waitcnt vmcnt(8)
	s_waitcnt lgkmcnt(0)
	s_barrier
	s_setprio 1
	v_mfma_f32_16x16x32_bf16 v[62:65], v[146:149], v[192:195], v[62:65]
	v_mfma_f32_16x16x32_bf16 v[58:61], v[166:169], v[192:195], v[58:61]
	v_mfma_f32_16x16x32_bf16 v[46:49], v[146:149], v[200:203], v[46:49]
	v_mfma_f32_16x16x32_bf16 v[42:45], v[166:169], v[200:203], v[42:45]
	v_mfma_f32_16x16x32_bf16 v[30:33], v[146:149], v[208:211], v[30:33]
	v_mfma_f32_16x16x32_bf16 v[26:29], v[166:169], v[208:211], v[26:29]
	v_mfma_f32_16x16x32_bf16 v[14:17], v[146:149], v[216:219], v[14:17]
	v_mfma_f32_16x16x32_bf16 v[10:13], v[166:169], v[216:219], v[10:13]
	v_mfma_f32_16x16x32_bf16 v[62:65], v[162:165], v[196:199], v[62:65]
	v_mfma_f32_16x16x32_bf16 v[58:61], v[170:173], v[196:199], v[58:61]
	v_mfma_f32_16x16x32_bf16 v[46:49], v[162:165], v[204:207], v[46:49]
	v_mfma_f32_16x16x32_bf16 v[42:45], v[170:173], v[204:207], v[42:45]
	v_mfma_f32_16x16x32_bf16 v[30:33], v[162:165], v[212:215], v[30:33]
	v_mfma_f32_16x16x32_bf16 v[26:29], v[170:173], v[212:215], v[26:29]
	v_mfma_f32_16x16x32_bf16 v[14:17], v[162:165], v[220:223], v[14:17]
	v_mfma_f32_16x16x32_bf16 v[10:13], v[170:173], v[220:223], v[10:13]
	s_setprio 0
	s_setprio 1
	v_mfma_f32_16x16x32_bf16 v[54:57], v[176:179], v[192:195], v[54:57]
	v_mfma_f32_16x16x32_bf16 v[50:53], v[184:187], v[192:195], v[50:53]
	v_mfma_f32_16x16x32_bf16 v[38:41], v[176:179], v[200:203], v[38:41]
	v_mfma_f32_16x16x32_bf16 v[34:37], v[184:187], v[200:203], v[34:37]
	v_mfma_f32_16x16x32_bf16 v[22:25], v[176:179], v[208:211], v[22:25]
	v_mfma_f32_16x16x32_bf16 v[18:21], v[184:187], v[208:211], v[18:21]
	v_mfma_f32_16x16x32_bf16 v[6:9], v[176:179], v[216:219], v[6:9]
	v_mfma_f32_16x16x32_bf16 v[2:5], v[184:187], v[216:219], v[2:5]
	v_mfma_f32_16x16x32_bf16 v[54:57], v[180:183], v[196:199], v[54:57]
	v_mfma_f32_16x16x32_bf16 v[50:53], v[188:191], v[196:199], v[50:53]
	v_mfma_f32_16x16x32_bf16 v[38:41], v[180:183], v[204:207], v[38:41]
	v_mfma_f32_16x16x32_bf16 v[34:37], v[188:191], v[204:207], v[34:37]
	v_mfma_f32_16x16x32_bf16 v[22:25], v[180:183], v[212:215], v[22:25]
	v_mfma_f32_16x16x32_bf16 v[18:21], v[188:191], v[212:215], v[18:21]
	v_mfma_f32_16x16x32_bf16 v[6:9], v[180:183], v[220:223], v[6:9]
	v_mfma_f32_16x16x32_bf16 v[2:5], v[188:191], v[220:223], v[2:5]
	s_setprio 0
	s_barrier
	s_add_i32 s42, s58, 2
	s_add_u32 s40, s40, 0x100
	s_addc_u32 s41, s41, 0
	s_add_u32 s56, s56, 0x100
	s_addc_u32 s57, s57, 0
	s_cmp_ge_u32 s58, s55
	s_mov_b32 s58, s42
	s_cbranch_scc0 .LBB0_566
	s_and_b64 vcc, exec, s[4:5]
	s_cbranch_vccz .LBB0_569
	s_barrier

.LBB0_791:
	ds_read_b128 v[158:161], v143
	ds_read_b128 v[162:165], v143 offset:1024
	ds_read_b128 v[166:169], v143 offset:2048
	ds_read_b128 v[176:179], v143 offset:3072
	ds_read_b128 v[180:183], v170
	ds_read_b128 v[184:187], v170 offset:1024
	ds_read_b128 v[188:191], v170 offset:2048
	ds_read_b128 v[192:195], v170 offset:3072
	s_add_u32 s40, s38, 0xfff80080
	s_addc_u32 s41, s39, -1
	s_cmp_eq_u32 s53, 28
	s_cselect_b32 s43, s1, s41
	s_cselect_b32 s42, s45, s40
	s_cselect_b32 s41, s35, s52
	s_cselect_b32 s40, s50, s51
	v_lshl_add_u64 v[152:153], s[38:39], 0, v[144:145]
	s_add_i32 m0, s23, 0xc000
	ds_read_b128 v[196:199], v171
	ds_read_b128 v[200:203], v171 offset:1024
	ds_read_b128 v[204:207], v171 offset:2048
	ds_read_b128 v[208:211], v171 offset:3072
	ds_read_b128 v[212:215], v171 offset:4096
	ds_read_b128 v[216:219], v171 offset:5120
	ds_read_b128 v[220:223], v171 offset:6144
	ds_read_b128 v[224:227], v171 offset:7168
	global_load_lds_dwordx4 v[152:153], off
	v_lshl_add_u64 v[152:153], s[38:39], 0, v[146:147]
	s_add_i32 m0, s23, 0xe000
	s_nop 0
	global_load_lds_dwordx4 v[152:153], off
	s_waitcnt vmcnt(8)
	s_waitcnt lgkmcnt(0)
	s_barrier
	s_setprio 1
	v_mfma_f32_16x16x32_bf16 v[126:129], v[158:161], v[196:199], v[126:129]
	v_mfma_f32_16x16x32_bf16 v[122:125], v[166:169], v[196:199], v[122:125]
	v_mfma_f32_16x16x32_bf16 v[110:113], v[158:161], v[204:207], v[110:113]
	v_mfma_f32_16x16x32_bf16 v[106:109], v[166:169], v[204:207], v[106:109]
	v_mfma_f32_16x16x32_bf16 v[94:97], v[158:161], v[212:215], v[94:97]
	v_mfma_f32_16x16x32_bf16 v[90:93], v[166:169], v[212:215], v[90:93]
	v_mfma_f32_16x16x32_bf16 v[78:81], v[158:161], v[220:223], v[78:81]
	v_mfma_f32_16x16x32_bf16 v[74:77], v[166:169], v[220:223], v[74:77]
	v_mfma_f32_16x16x32_bf16 v[126:129], v[162:165], v[200:203], v[126:129]
	v_mfma_f32_16x16x32_bf16 v[122:125], v[176:179], v[200:203], v[122:125]
	v_mfma_f32_16x16x32_bf16 v[110:113], v[162:165], v[208:211], v[110:113]
	v_mfma_f32_16x16x32_bf16 v[106:109], v[176:179], v[208:211], v[106:109]
	v_mfma_f32_16x16x32_bf16 v[94:97], v[162:165], v[216:219], v[94:97]
	v_mfma_f32_16x16x32_bf16 v[90:93], v[176:179], v[216:219], v[90:93]
	v_mfma_f32_16x16x32_bf16 v[78:81], v[162:165], v[224:227], v[78:81]
	v_mfma_f32_16x16x32_bf16 v[74:77], v[176:179], v[224:227], v[74:77]
	s_setprio 0
	s_setprio 1
	v_mfma_f32_16x16x32_bf16 v[118:121], v[180:183], v[196:199], v[118:121]
	v_mfma_f32_16x16x32_bf16 v[114:117], v[188:191], v[196:199], v[114:117]
	v_mfma_f32_16x16x32_bf16 v[102:105], v[180:183], v[204:207], v[102:105]
	v_mfma_f32_16x16x32_bf16 v[98:101], v[188:191], v[204:207], v[98:101]
	v_mfma_f32_16x16x32_bf16 v[86:89], v[180:183], v[212:215], v[86:89]
	v_mfma_f32_16x16x32_bf16 v[82:85], v[188:191], v[212:215], v[82:85]
	v_mfma_f32_16x16x32_bf16 v[70:73], v[180:183], v[220:223], v[70:73]
	v_mfma_f32_16x16x32_bf16 v[66:69], v[188:191], v[220:223], v[66:69]
	v_mfma_f32_16x16x32_bf16 v[118:121], v[184:187], v[200:203], v[118:121]
	v_mfma_f32_16x16x32_bf16 v[114:117], v[192:195], v[200:203], v[114:117]
	v_mfma_f32_16x16x32_bf16 v[102:105], v[184:187], v[208:211], v[102:105]
	v_mfma_f32_16x16x32_bf16 v[98:101], v[192:195], v[208:211], v[98:101]
	v_mfma_f32_16x16x32_bf16 v[86:89], v[184:187], v[216:219], v[86:89]
	v_mfma_f32_16x16x32_bf16 v[82:85], v[192:195], v[216:219], v[82:85]
	v_mfma_f32_16x16x32_bf16 v[70:73], v[184:187], v[224:227], v[70:73]
	v_mfma_f32_16x16x32_bf16 v[66:69], v[192:195], v[224:227], v[66:69]
	s_setprio 0
	s_barrier
	s_add_i32 s54, s59, s22
	v_lshl_add_u64 v[152:153], s[40:41], 0, v[132:133]
	s_mov_b32 m0, s54
	ds_read_b128 v[196:199], v171 offset:16384
	ds_read_b128 v[200:203], v171 offset:17408
	ds_read_b128 v[204:207], v171 offset:18432
	ds_read_b128 v[208:211], v171 offset:19456
	ds_read_b128 v[212:215], v171 offset:20480
	ds_read_b128 v[216:219], v171 offset:21504
	ds_read_b128 v[220:223], v171 offset:22528
	ds_read_b128 v[224:227], v171 offset:23552
	global_load_lds_dwordx4 v[152:153], off
	s_add_i32 m0, s54, 0x2000
	s_add_u32 s54, s40, 0x80000
	v_lshl_add_u64 v[172:173], s[40:41], 0, v[136:137]
	s_addc_u32 s55, s41, 0
	s_add_i32 s56, s60, s22
	global_load_lds_dwordx4 v[172:173], off
	v_lshl_add_u64 v[228:229], s[54:55], 0, v[132:133]
	s_mov_b32 m0, s56
	v_lshl_add_u64 v[230:231], s[42:43], 0, v[134:135]
	global_load_lds_dwordx4 v[228:229], off
	v_lshl_add_u64 v[228:229], s[54:55], 0, v[136:137]
	s_add_i32 m0, s56, 0x2000
	s_nop 0
	global_load_lds_dwordx4 v[228:229], off
	v_lshl_add_u64 v[228:229], s[42:43], 0, v[130:131]
	s_mov_b32 m0, s23
	s_nop 0
	global_load_lds_dwordx4 v[228:229], off
	s_mov_b32 m0, s24
	s_nop 0
	global_load_lds_dwordx4 v[230:231], off
	s_waitcnt vmcnt(8)
	s_waitcnt lgkmcnt(0)
	s_barrier
	s_setprio 1
	v_mfma_f32_16x16x32_bf16 v[62:65], v[158:161], v[196:199], v[62:65]
	v_mfma_f32_16x16x32_bf16 v[58:61], v[166:169], v[196:199], v[58:61]
	v_mfma_f32_16x16x32_bf16 v[46:49], v[158:161], v[204:207], v[46:49]
	v_mfma_f32_16x16x32_bf16 v[42:45], v[166:169], v[204:207], v[42:45]
	v_mfma_f32_16x16x32_bf16 v[30:33], v[158:161], v[212:215], v[30:33]
	v_mfma_f32_16x16x32_bf16 v[26:29], v[166:169], v[212:215], v[26:29]
	v_mfma_f32_16x16x32_bf16 v[14:17], v[158:161], v[220:223], v[14:17]
	v_mfma_f32_16x16x32_bf16 v[10:13], v[166:169], v[220:223], v[10:13]
	v_mfma_f32_16x16x32_bf16 v[62:65], v[162:165], v[200:203], v[62:65]
	v_mfma_f32_16x16x32_bf16 v[58:61], v[176:179], v[200:203], v[58:61]
	v_mfma_f32_16x16x32_bf16 v[46:49], v[162:165], v[208:211], v[46:49]
	v_mfma_f32_16x16x32_bf16 v[42:45], v[176:179], v[208:211], v[42:45]
	v_mfma_f32_16x16x32_bf16 v[30:33], v[162:165], v[216:219], v[30:33]
	v_mfma_f32_16x16x32_bf16 v[26:29], v[176:179], v[216:219], v[26:29]
	v_mfma_f32_16x16x32_bf16 v[14:17], v[162:165], v[224:227], v[14:17]
	v_mfma_f32_16x16x32_bf16 v[10:13], v[176:179], v[224:227], v[10:13]
	s_setprio 0
	s_setprio 1
	v_mfma_f32_16x16x32_bf16 v[54:57], v[180:183], v[196:199], v[54:57]
	v_mfma_f32_16x16x32_bf16 v[50:53], v[188:191], v[196:199], v[50:53]
	v_mfma_f32_16x16x32_bf16 v[38:41], v[180:183], v[204:207], v[38:41]
	v_mfma_f32_16x16x32_bf16 v[34:37], v[188:191], v[204:207], v[34:37]
	v_mfma_f32_16x16x32_bf16 v[22:25], v[180:183], v[212:215], v[22:25]
	v_mfma_f32_16x16x32_bf16 v[18:21], v[188:191], v[212:215], v[18:21]
	v_mfma_f32_16x16x32_bf16 v[6:9], v[180:183], v[220:223], v[6:9]
	v_mfma_f32_16x16x32_bf16 v[2:5], v[188:191], v[220:223], v[2:5]
	v_mfma_f32_16x16x32_bf16 v[54:57], v[184:187], v[200:203], v[54:57]
	v_mfma_f32_16x16x32_bf16 v[50:53], v[192:195], v[200:203], v[50:53]
	v_mfma_f32_16x16x32_bf16 v[38:41], v[184:187], v[208:211], v[38:41]
	v_mfma_f32_16x16x32_bf16 v[34:37], v[192:195], v[208:211], v[34:37]
	v_mfma_f32_16x16x32_bf16 v[22:25], v[184:187], v[216:219], v[22:25]
	v_mfma_f32_16x16x32_bf16 v[18:21], v[192:195], v[216:219], v[18:21]
	v_mfma_f32_16x16x32_bf16 v[6:9], v[184:187], v[224:227], v[6:9]
	v_mfma_f32_16x16x32_bf16 v[2:5], v[192:195], v[224:227], v[2:5]
	s_setprio 0
	s_barrier
	s_add_i32 s54, 0, 0x18000
	v_add_u32_e32 v138, s54, v141
	s_add_i32 s55, 0, 0x1c000
	ds_read_b128 v[158:161], v138
	ds_read_b128 v[162:165], v138 offset:1024
	ds_read_b128 v[166:169], v138 offset:2048
	ds_read_b128 v[176:179], v138 offset:3072
	v_add_u32_e32 v138, s55, v141
	ds_read_b128 v[180:183], v138
	ds_read_b128 v[184:187], v138 offset:1024
	ds_read_b128 v[188:191], v138 offset:2048
	ds_read_b128 v[192:195], v138 offset:3072
	s_add_u32 s42, s42, 0x80000
	s_addc_u32 s43, s43, 0
	s_mov_b32 m0, s25
	v_lshl_add_u64 v[232:233], s[42:43], 0, v[130:131]
	ds_read_b128 v[196:199], v171 offset:32768
	ds_read_b128 v[200:203], v171 offset:33792
	ds_read_b128 v[204:207], v171 offset:34816
	ds_read_b128 v[208:211], v171 offset:35840
	ds_read_b128 v[212:215], v171 offset:36864
	ds_read_b128 v[216:219], v171 offset:37888
	ds_read_b128 v[220:223], v171 offset:38912
	ds_read_b128 v[224:227], v171 offset:39936
	global_load_lds_dwordx4 v[232:233], off
	v_lshl_add_u64 v[232:233], s[42:43], 0, v[134:135]
	s_mov_b32 m0, s26
	s_nop 0
	global_load_lds_dwordx4 v[232:233], off
	s_waitcnt vmcnt(8)
	s_waitcnt lgkmcnt(0)
	s_barrier
	s_setprio 1
	v_mfma_f32_16x16x32_bf16 v[126:129], v[158:161], v[196:199], v[126:129]
	v_mfma_f32_16x16x32_bf16 v[122:125], v[166:169], v[196:199], v[122:125]
	v_mfma_f32_16x16x32_bf16 v[110:113], v[158:161], v[204:207], v[110:113]
	v_mfma_f32_16x16x32_bf16 v[106:109], v[166:169], v[204:207], v[106:109]
	v_mfma_f32_16x16x32_bf16 v[94:97], v[158:161], v[212:215], v[94:97]
	v_mfma_f32_16x16x32_bf16 v[90:93], v[166:169], v[212:215], v[90:93]
	v_mfma_f32_16x16x32_bf16 v[78:81], v[158:161], v[220:223], v[78:81]
	v_mfma_f32_16x16x32_bf16 v[74:77], v[166:169], v[220:223], v[74:77]
	v_mfma_f32_16x16x32_bf16 v[126:129], v[162:165], v[200:203], v[126:129]
	v_mfma_f32_16x16x32_bf16 v[122:125], v[176:179], v[200:203], v[122:125]
	v_mfma_f32_16x16x32_bf16 v[110:113], v[162:165], v[208:211], v[110:113]
	v_mfma_f32_16x16x32_bf16 v[106:109], v[176:179], v[208:211], v[106:109]
	v_mfma_f32_16x16x32_bf16 v[94:97], v[162:165], v[216:219], v[94:97]
	v_mfma_f32_16x16x32_bf16 v[90:93], v[176:179], v[216:219], v[90:93]
	v_mfma_f32_16x16x32_bf16 v[78:81], v[162:165], v[224:227], v[78:81]
	v_mfma_f32_16x16x32_bf16 v[74:77], v[176:179], v[224:227], v[74:77]
	s_setprio 0
	s_setprio 1
	v_mfma_f32_16x16x32_bf16 v[118:121], v[180:183], v[196:199], v[118:121]
	v_mfma_f32_16x16x32_bf16 v[114:117], v[188:191], v[196:199], v[114:117]
	v_mfma_f32_16x16x32_bf16 v[102:105], v[180:183], v[204:207], v[102:105]
	v_mfma_f32_16x16x32_bf16 v[98:101], v[188:191], v[204:207], v[98:101]
	v_mfma_f32_16x16x32_bf16 v[86:89], v[180:183], v[212:215], v[86:89]
	v_mfma_f32_16x16x32_bf16 v[82:85], v[188:191], v[212:215], v[82:85]
	v_mfma_f32_16x16x32_bf16 v[70:73], v[180:183], v[220:223], v[70:73]
	v_mfma_f32_16x16x32_bf16 v[66:69], v[188:191], v[220:223], v[66:69]
	v_mfma_f32_16x16x32_bf16 v[118:121], v[184:187], v[200:203], v[118:121]
	v_mfma_f32_16x16x32_bf16 v[114:117], v[192:195], v[200:203], v[114:117]
	v_mfma_f32_16x16x32_bf16 v[102:105], v[184:187], v[208:211], v[102:105]
	v_mfma_f32_16x16x32_bf16 v[98:101], v[192:195], v[208:211], v[98:101]
	v_mfma_f32_16x16x32_bf16 v[86:89], v[184:187], v[216:219], v[86:89]
	v_mfma_f32_16x16x32_bf16 v[82:85], v[192:195], v[216:219], v[82:85]
	v_mfma_f32_16x16x32_bf16 v[70:73], v[184:187], v[224:227], v[70:73]
	v_mfma_f32_16x16x32_bf16 v[66:69], v[192:195], v[224:227], v[66:69]
	s_setprio 0
	s_barrier
	s_add_i32 s42, s54, s22
	v_lshl_add_u64 v[152:153], v[152:153], 0, s[10:11]
	s_mov_b32 m0, s42
	ds_read_b128 v[196:199], v171 offset:49152
	ds_read_b128 v[200:203], v171 offset:50176
	ds_read_b128 v[204:207], v171 offset:51200
	ds_read_b128 v[208:211], v171 offset:52224
	ds_read_b128 v[212:215], v171 offset:53248
	ds_read_b128 v[216:219], v171 offset:54272
	ds_read_b128 v[220:223], v171 offset:55296
	ds_read_b128 v[224:227], v171 offset:56320
	global_load_lds_dwordx4 v[152:153], off
	s_add_i32 m0, s42, 0x2000
	s_add_u32 s40, s40, 0x80080
	v_lshl_add_u64 v[152:153], v[172:173], 0, s[10:11]
	s_addc_u32 s41, s41, 0
	s_add_i32 s42, s55, s22
	global_load_lds_dwordx4 v[152:153], off
	v_lshl_add_u64 v[152:153], s[40:41], 0, v[132:133]
	s_mov_b32 m0, s42
	s_nop 0
	global_load_lds_dwordx4 v[152:153], off
	v_lshl_add_u64 v[152:153], s[40:41], 0, v[136:137]
	s_add_i32 m0, s42, 0x2000
	s_nop 0
	global_load_lds_dwordx4 v[152:153], off
	v_lshl_add_u64 v[152:153], v[228:229], 0, s[10:11]
	s_mov_b32 m0, s27
	s_nop 0
	global_load_lds_dwordx4 v[152:153], off
	v_lshl_add_u64 v[152:153], v[230:231], 0, s[10:11]
	s_mov_b32 m0, s33
	s_nop 0
	global_load_lds_dwordx4 v[152:153], off
	s_waitcnt vmcnt(8)
	s_waitcnt lgkmcnt(0)
	s_barrier
	s_setprio 1
	v_mfma_f32_16x16x32_bf16 v[62:65], v[158:161], v[196:199], v[62:65]
	v_mfma_f32_16x16x32_bf16 v[58:61], v[166:169], v[196:199], v[58:61]
	v_mfma_f32_16x16x32_bf16 v[46:49], v[158:161], v[204:207], v[46:49]
	v_mfma_f32_16x16x32_bf16 v[42:45], v[166:169], v[204:207], v[42:45]
	v_mfma_f32_16x16x32_bf16 v[30:33], v[158:161], v[212:215], v[30:33]
	v_mfma_f32_16x16x32_bf16 v[26:29], v[166:169], v[212:215], v[26:29]
	v_mfma_f32_16x16x32_bf16 v[14:17], v[158:161], v[220:223], v[14:17]
	v_mfma_f32_16x16x32_bf16 v[10:13], v[166:169], v[220:223], v[10:13]
	v_mfma_f32_16x16x32_bf16 v[62:65], v[162:165], v[200:203], v[62:65]
	v_mfma_f32_16x16x32_bf16 v[58:61], v[176:179], v[200:203], v[58:61]
	v_mfma_f32_16x16x32_bf16 v[46:49], v[162:165], v[208:211], v[46:49]
	v_mfma_f32_16x16x32_bf16 v[42:45], v[176:179], v[208:211], v[42:45]
	v_mfma_f32_16x16x32_bf16 v[30:33], v[162:165], v[216:219], v[30:33]
	v_mfma_f32_16x16x32_bf16 v[26:29], v[176:179], v[216:219], v[26:29]
	v_mfma_f32_16x16x32_bf16 v[14:17], v[162:165], v[224:227], v[14:17]
	v_mfma_f32_16x16x32_bf16 v[10:13], v[176:179], v[224:227], v[10:13]
	s_setprio 0
	s_setprio 1
	v_mfma_f32_16x16x32_bf16 v[54:57], v[180:183], v[196:199], v[54:57]
	v_mfma_f32_16x16x32_bf16 v[50:53], v[188:191], v[196:199], v[50:53]
	v_mfma_f32_16x16x32_bf16 v[38:41], v[180:183], v[204:207], v[38:41]
	v_mfma_f32_16x16x32_bf16 v[34:37], v[188:191], v[204:207], v[34:37]
	v_mfma_f32_16x16x32_bf16 v[22:25], v[180:183], v[212:215], v[22:25]
	v_mfma_f32_16x16x32_bf16 v[18:21], v[188:191], v[212:215], v[18:21]
	v_mfma_f32_16x16x32_bf16 v[6:9], v[180:183], v[220:223], v[6:9]
	v_mfma_f32_16x16x32_bf16 v[2:5], v[188:191], v[220:223], v[2:5]
	v_mfma_f32_16x16x32_bf16 v[54:57], v[184:187], v[200:203], v[54:57]
	v_mfma_f32_16x16x32_bf16 v[50:53], v[192:195], v[200:203], v[50:53]
	v_mfma_f32_16x16x32_bf16 v[38:41], v[184:187], v[208:211], v[38:41]
	v_mfma_f32_16x16x32_bf16 v[34:37], v[192:195], v[208:211], v[34:37]
	v_mfma_f32_16x16x32_bf16 v[22:25], v[184:187], v[216:219], v[22:25]
	v_mfma_f32_16x16x32_bf16 v[18:21], v[192:195], v[216:219], v[18:21]
	v_mfma_f32_16x16x32_bf16 v[6:9], v[184:187], v[224:227], v[6:9]
	v_mfma_f32_16x16x32_bf16 v[2:5], v[192:195], v[224:227], v[2:5]
	s_setprio 0
	s_barrier
	s_add_i32 s53, s53, 2
	s_add_u32 s38, s38, 0x100
	s_addc_u32 s39, s39, 0
	s_add_u32 s51, s51, 0x100
	s_addc_u32 s52, s52, 0
	s_cmp_gt_u32 s53, 29
	s_cbranch_scc0 .LBB0_791
	s_and_b64 vcc, exec, s[16:17]
	s_cbranch_vccz .LBB0_794
	s_barrier

.LBB0_1545:
	ds_read_b128 v[146:149], v158
	ds_read_b128 v[162:165], v158 offset:1024
	ds_read_b128 v[166:169], v158 offset:2048
	ds_read_b128 v[170:173], v158 offset:3072
	ds_read_b128 v[176:179], v159
	ds_read_b128 v[180:183], v159 offset:1024
	ds_read_b128 v[184:187], v159 offset:2048
	ds_read_b128 v[188:191], v159 offset:3072
	s_add_u32 s36, s34, 0xfff80080
	s_addc_u32 s37, s35, -1
	s_cmp_eq_u32 s51, s54
	s_cselect_b32 s39, s11, s37
	s_cselect_b32 s38, s19, s36
	s_cselect_b32 s37, s9, s53
	s_cselect_b32 s36, s21, s52
	v_lshl_add_u64 v[150:151], s[34:35], 0, v[138:139]
	s_add_i32 m0, s25, 0xc000
	ds_read_b128 v[192:195], v160
	ds_read_b128 v[196:199], v160 offset:1024
	ds_read_b128 v[200:203], v160 offset:2048
	ds_read_b128 v[204:207], v160 offset:3072
	ds_read_b128 v[208:211], v160 offset:4096
	ds_read_b128 v[212:215], v160 offset:5120
	ds_read_b128 v[216:219], v160 offset:6144
	ds_read_b128 v[220:223], v160 offset:7168
	global_load_lds_dwordx4 v[150:151], off
	v_lshl_add_u64 v[150:151], s[34:35], 0, v[140:141]
	s_add_i32 m0, s25, 0xe000
	s_nop 0
	global_load_lds_dwordx4 v[150:151], off
	s_waitcnt vmcnt(8)
	s_waitcnt lgkmcnt(0)
	s_barrier
	s_setprio 1
	v_mfma_f32_16x16x32_bf16 v[126:129], v[146:149], v[192:195], v[126:129]
	v_mfma_f32_16x16x32_bf16 v[122:125], v[166:169], v[192:195], v[122:125]
	v_mfma_f32_16x16x32_bf16 v[110:113], v[146:149], v[200:203], v[110:113]
	v_mfma_f32_16x16x32_bf16 v[106:109], v[166:169], v[200:203], v[106:109]
	v_mfma_f32_16x16x32_bf16 v[94:97], v[146:149], v[208:211], v[94:97]
	v_mfma_f32_16x16x32_bf16 v[90:93], v[166:169], v[208:211], v[90:93]
	v_mfma_f32_16x16x32_bf16 v[78:81], v[146:149], v[216:219], v[78:81]
	v_mfma_f32_16x16x32_bf16 v[74:77], v[166:169], v[216:219], v[74:77]
	v_mfma_f32_16x16x32_bf16 v[126:129], v[162:165], v[196:199], v[126:129]
	v_mfma_f32_16x16x32_bf16 v[122:125], v[170:173], v[196:199], v[122:125]
	v_mfma_f32_16x16x32_bf16 v[110:113], v[162:165], v[204:207], v[110:113]
	v_mfma_f32_16x16x32_bf16 v[106:109], v[170:173], v[204:207], v[106:109]
	v_mfma_f32_16x16x32_bf16 v[94:97], v[162:165], v[212:215], v[94:97]
	v_mfma_f32_16x16x32_bf16 v[90:93], v[170:173], v[212:215], v[90:93]
	v_mfma_f32_16x16x32_bf16 v[78:81], v[162:165], v[220:223], v[78:81]
	v_mfma_f32_16x16x32_bf16 v[74:77], v[170:173], v[220:223], v[74:77]
	s_setprio 0
	s_setprio 1
	v_mfma_f32_16x16x32_bf16 v[118:121], v[176:179], v[192:195], v[118:121]
	v_mfma_f32_16x16x32_bf16 v[114:117], v[184:187], v[192:195], v[114:117]
	v_mfma_f32_16x16x32_bf16 v[102:105], v[176:179], v[200:203], v[102:105]
	v_mfma_f32_16x16x32_bf16 v[98:101], v[184:187], v[200:203], v[98:101]
	v_mfma_f32_16x16x32_bf16 v[86:89], v[176:179], v[208:211], v[86:89]
	v_mfma_f32_16x16x32_bf16 v[82:85], v[184:187], v[208:211], v[82:85]
	v_mfma_f32_16x16x32_bf16 v[70:73], v[176:179], v[216:219], v[70:73]
	v_mfma_f32_16x16x32_bf16 v[66:69], v[184:187], v[216:219], v[66:69]
	v_mfma_f32_16x16x32_bf16 v[118:121], v[180:183], v[196:199], v[118:121]
	v_mfma_f32_16x16x32_bf16 v[114:117], v[188:191], v[196:199], v[114:117]
	v_mfma_f32_16x16x32_bf16 v[102:105], v[180:183], v[204:207], v[102:105]
	v_mfma_f32_16x16x32_bf16 v[98:101], v[188:191], v[204:207], v[98:101]
	v_mfma_f32_16x16x32_bf16 v[86:89], v[180:183], v[212:215], v[86:89]
	v_mfma_f32_16x16x32_bf16 v[82:85], v[188:191], v[212:215], v[82:85]
	v_mfma_f32_16x16x32_bf16 v[70:73], v[180:183], v[220:223], v[70:73]
	v_mfma_f32_16x16x32_bf16 v[66:69], v[188:191], v[220:223], v[66:69]
	s_setprio 0
	s_barrier
	s_add_i32 s55, s45, s24
	v_lshl_add_u64 v[150:151], s[36:37], 0, v[132:133]
	s_mov_b32 m0, s55
	ds_read_b128 v[192:195], v160 offset:16384
	ds_read_b128 v[196:199], v160 offset:17408
	ds_read_b128 v[200:203], v160 offset:18432
	ds_read_b128 v[204:207], v160 offset:19456
	ds_read_b128 v[208:211], v160 offset:20480
	ds_read_b128 v[212:215], v160 offset:21504
	ds_read_b128 v[216:219], v160 offset:22528
	ds_read_b128 v[220:223], v160 offset:23552
	global_load_lds_dwordx4 v[150:151], off
	s_add_i32 m0, s55, 0x2000
	s_add_u32 s56, s36, 0x80000
	v_lshl_add_u64 v[224:225], s[36:37], 0, v[136:137]
	s_addc_u32 s57, s37, 0
	s_add_i32 s55, s46, s24
	global_load_lds_dwordx4 v[224:225], off
	v_lshl_add_u64 v[226:227], s[56:57], 0, v[132:133]
	s_mov_b32 m0, s55
	v_lshl_add_u64 v[228:229], s[38:39], 0, v[134:135]
	global_load_lds_dwordx4 v[226:227], off
	v_lshl_add_u64 v[226:227], s[56:57], 0, v[136:137]
	s_add_i32 m0, s55, 0x2000
	s_nop 0
	global_load_lds_dwordx4 v[226:227], off
	v_lshl_add_u64 v[226:227], s[38:39], 0, v[130:131]
	s_mov_b32 m0, s25
	s_nop 0
	global_load_lds_dwordx4 v[226:227], off
	s_mov_b32 m0, s26
	s_nop 0
	global_load_lds_dwordx4 v[228:229], off
	s_waitcnt vmcnt(8)
	s_waitcnt lgkmcnt(0)
	s_barrier
	s_setprio 1
	v_mfma_f32_16x16x32_bf16 v[62:65], v[146:149], v[192:195], v[62:65]
	v_mfma_f32_16x16x32_bf16 v[58:61], v[166:169], v[192:195], v[58:61]
	v_mfma_f32_16x16x32_bf16 v[46:49], v[146:149], v[200:203], v[46:49]
	v_mfma_f32_16x16x32_bf16 v[42:45], v[166:169], v[200:203], v[42:45]
	v_mfma_f32_16x16x32_bf16 v[30:33], v[146:149], v[208:211], v[30:33]
	v_mfma_f32_16x16x32_bf16 v[26:29], v[166:169], v[208:211], v[26:29]
	v_mfma_f32_16x16x32_bf16 v[14:17], v[146:149], v[216:219], v[14:17]
	v_mfma_f32_16x16x32_bf16 v[10:13], v[166:169], v[216:219], v[10:13]
	v_mfma_f32_16x16x32_bf16 v[62:65], v[162:165], v[196:199], v[62:65]
	v_mfma_f32_16x16x32_bf16 v[58:61], v[170:173], v[196:199], v[58:61]
	v_mfma_f32_16x16x32_bf16 v[46:49], v[162:165], v[204:207], v[46:49]
	v_mfma_f32_16x16x32_bf16 v[42:45], v[170:173], v[204:207], v[42:45]
	v_mfma_f32_16x16x32_bf16 v[30:33], v[162:165], v[212:215], v[30:33]
	v_mfma_f32_16x16x32_bf16 v[26:29], v[170:173], v[212:215], v[26:29]
	v_mfma_f32_16x16x32_bf16 v[14:17], v[162:165], v[220:223], v[14:17]
	v_mfma_f32_16x16x32_bf16 v[10:13], v[170:173], v[220:223], v[10:13]
	s_setprio 0
	s_setprio 1
	v_mfma_f32_16x16x32_bf16 v[54:57], v[176:179], v[192:195], v[54:57]
	v_mfma_f32_16x16x32_bf16 v[50:53], v[184:187], v[192:195], v[50:53]
	v_mfma_f32_16x16x32_bf16 v[38:41], v[176:179], v[200:203], v[38:41]
	v_mfma_f32_16x16x32_bf16 v[34:37], v[184:187], v[200:203], v[34:37]
	v_mfma_f32_16x16x32_bf16 v[22:25], v[176:179], v[208:211], v[22:25]
	v_mfma_f32_16x16x32_bf16 v[18:21], v[184:187], v[208:211], v[18:21]
	v_mfma_f32_16x16x32_bf16 v[6:9], v[176:179], v[216:219], v[6:9]
	v_mfma_f32_16x16x32_bf16 v[2:5], v[184:187], v[216:219], v[2:5]
	v_mfma_f32_16x16x32_bf16 v[54:57], v[180:183], v[196:199], v[54:57]
	v_mfma_f32_16x16x32_bf16 v[50:53], v[188:191], v[196:199], v[50:53]
	v_mfma_f32_16x16x32_bf16 v[38:41], v[180:183], v[204:207], v[38:41]
	v_mfma_f32_16x16x32_bf16 v[34:37], v[188:191], v[204:207], v[34:37]
	v_mfma_f32_16x16x32_bf16 v[22:25], v[180:183], v[212:215], v[22:25]
	v_mfma_f32_16x16x32_bf16 v[18:21], v[188:191], v[212:215], v[18:21]
	v_mfma_f32_16x16x32_bf16 v[6:9], v[180:183], v[220:223], v[6:9]
	v_mfma_f32_16x16x32_bf16 v[2:5], v[188:191], v[220:223], v[2:5]
	s_setprio 0
	s_barrier
	s_add_i32 s55, 0, 0x18000
	v_add_u32_e32 v161, s55, v152
	s_add_i32 s56, 0, 0x1c000
	ds_read_b128 v[146:149], v161
	ds_read_b128 v[162:165], v161 offset:1024
	ds_read_b128 v[166:169], v161 offset:2048
	ds_read_b128 v[170:173], v161 offset:3072
	v_add_u32_e32 v161, s56, v152
	ds_read_b128 v[176:179], v161
	ds_read_b128 v[180:183], v161 offset:1024
	ds_read_b128 v[184:187], v161 offset:2048
	ds_read_b128 v[188:191], v161 offset:3072
	s_add_u32 s38, s38, 0x80000
	s_addc_u32 s39, s39, 0
	s_mov_b32 m0, s27
	v_lshl_add_u64 v[230:231], s[38:39], 0, v[130:131]
	ds_read_b128 v[192:195], v160 offset:32768
	ds_read_b128 v[196:199], v160 offset:33792
	ds_read_b128 v[200:203], v160 offset:34816
	ds_read_b128 v[204:207], v160 offset:35840
	ds_read_b128 v[208:211], v160 offset:36864
	ds_read_b128 v[212:215], v160 offset:37888
	ds_read_b128 v[216:219], v160 offset:38912
	ds_read_b128 v[220:223], v160 offset:39936
	global_load_lds_dwordx4 v[230:231], off
	v_lshl_add_u64 v[230:231], s[38:39], 0, v[134:135]
	s_mov_b32 m0, s33
	s_nop 0
	global_load_lds_dwordx4 v[230:231], off
	s_waitcnt vmcnt(8)
	s_waitcnt lgkmcnt(0)
	s_barrier
	s_setprio 1
	v_mfma_f32_16x16x32_bf16 v[126:129], v[146:149], v[192:195], v[126:129]
	v_mfma_f32_16x16x32_bf16 v[122:125], v[166:169], v[192:195], v[122:125]
	v_mfma_f32_16x16x32_bf16 v[110:113], v[146:149], v[200:203], v[110:113]
	v_mfma_f32_16x16x32_bf16 v[106:109], v[166:169], v[200:203], v[106:109]
	v_mfma_f32_16x16x32_bf16 v[94:97], v[146:149], v[208:211], v[94:97]
	v_mfma_f32_16x16x32_bf16 v[90:93], v[166:169], v[208:211], v[90:93]
	v_mfma_f32_16x16x32_bf16 v[78:81], v[146:149], v[216:219], v[78:81]
	v_mfma_f32_16x16x32_bf16 v[74:77], v[166:169], v[216:219], v[74:77]
	v_mfma_f32_16x16x32_bf16 v[126:129], v[162:165], v[196:199], v[126:129]
	v_mfma_f32_16x16x32_bf16 v[122:125], v[170:173], v[196:199], v[122:125]
	v_mfma_f32_16x16x32_bf16 v[110:113], v[162:165], v[204:207], v[110:113]
	v_mfma_f32_16x16x32_bf16 v[106:109], v[170:173], v[204:207], v[106:109]
	v_mfma_f32_16x16x32_bf16 v[94:97], v[162:165], v[212:215], v[94:97]
	v_mfma_f32_16x16x32_bf16 v[90:93], v[170:173], v[212:215], v[90:93]
	v_mfma_f32_16x16x32_bf16 v[78:81], v[162:165], v[220:223], v[78:81]
	v_mfma_f32_16x16x32_bf16 v[74:77], v[170:173], v[220:223], v[74:77]
	s_setprio 0
	s_setprio 1
	v_mfma_f32_16x16x32_bf16 v[118:121], v[176:179], v[192:195], v[118:121]
	v_mfma_f32_16x16x32_bf16 v[114:117], v[184:187], v[192:195], v[114:117]
	v_mfma_f32_16x16x32_bf16 v[102:105], v[176:179], v[200:203], v[102:105]
	v_mfma_f32_16x16x32_bf16 v[98:101], v[184:187], v[200:203], v[98:101]
	v_mfma_f32_16x16x32_bf16 v[86:89], v[176:179], v[208:211], v[86:89]
	v_mfma_f32_16x16x32_bf16 v[82:85], v[184:187], v[208:211], v[82:85]
	v_mfma_f32_16x16x32_bf16 v[70:73], v[176:179], v[216:219], v[70:73]
	v_mfma_f32_16x16x32_bf16 v[66:69], v[184:187], v[216:219], v[66:69]
	v_mfma_f32_16x16x32_bf16 v[118:121], v[180:183], v[196:199], v[118:121]
	v_mfma_f32_16x16x32_bf16 v[114:117], v[188:191], v[196:199], v[114:117]
	v_mfma_f32_16x16x32_bf16 v[102:105], v[180:183], v[204:207], v[102:105]
	v_mfma_f32_16x16x32_bf16 v[98:101], v[188:191], v[204:207], v[98:101]
	v_mfma_f32_16x16x32_bf16 v[86:89], v[180:183], v[212:215], v[86:89]
	v_mfma_f32_16x16x32_bf16 v[82:85], v[188:191], v[212:215], v[82:85]
	v_mfma_f32_16x16x32_bf16 v[70:73], v[180:183], v[220:223], v[70:73]
	v_mfma_f32_16x16x32_bf16 v[66:69], v[188:191], v[220:223], v[66:69]
	s_setprio 0
	s_barrier
	s_add_i32 s38, s55, s24
	v_lshl_add_u64 v[150:151], v[150:151], 0, s[2:3]
	s_mov_b32 m0, s38
	ds_read_b128 v[192:195], v160 offset:49152
	ds_read_b128 v[196:199], v160 offset:50176
	ds_read_b128 v[200:203], v160 offset:51200
	ds_read_b128 v[204:207], v160 offset:52224
	ds_read_b128 v[208:211], v160 offset:53248
	ds_read_b128 v[212:215], v160 offset:54272
	ds_read_b128 v[216:219], v160 offset:55296
	ds_read_b128 v[220:223], v160 offset:56320
	global_load_lds_dwordx4 v[150:151], off
	s_add_i32 m0, s38, 0x2000
	s_add_u32 s36, s36, 0x80080
	v_lshl_add_u64 v[150:151], v[224:225], 0, s[2:3]
	s_addc_u32 s37, s37, 0
	s_add_i32 s38, s56, s24
	global_load_lds_dwordx4 v[150:151], off
	v_lshl_add_u64 v[150:151], s[36:37], 0, v[132:133]
	s_mov_b32 m0, s38
	s_nop 0
	global_load_lds_dwordx4 v[150:151], off
	v_lshl_add_u64 v[150:151], s[36:37], 0, v[136:137]
	s_add_i32 m0, s38, 0x2000
	s_nop 0
	global_load_lds_dwordx4 v[150:151], off
	v_lshl_add_u64 v[150:151], v[226:227], 0, s[2:3]
	s_mov_b32 m0, s41
	s_nop 0
	global_load_lds_dwordx4 v[150:151], off
	v_lshl_add_u64 v[150:151], v[228:229], 0, s[2:3]
	s_mov_b32 m0, s42
	s_nop 0
	global_load_lds_dwordx4 v[150:151], off
	s_waitcnt vmcnt(8)
	s_waitcnt lgkmcnt(0)
	s_barrier
	s_setprio 1
	v_mfma_f32_16x16x32_bf16 v[62:65], v[146:149], v[192:195], v[62:65]
	v_mfma_f32_16x16x32_bf16 v[58:61], v[166:169], v[192:195], v[58:61]
	v_mfma_f32_16x16x32_bf16 v[46:49], v[146:149], v[200:203], v[46:49]
	v_mfma_f32_16x16x32_bf16 v[42:45], v[166:169], v[200:203], v[42:45]
	v_mfma_f32_16x16x32_bf16 v[30:33], v[146:149], v[208:211], v[30:33]
	v_mfma_f32_16x16x32_bf16 v[26:29], v[166:169], v[208:211], v[26:29]
	v_mfma_f32_16x16x32_bf16 v[14:17], v[146:149], v[216:219], v[14:17]
	v_mfma_f32_16x16x32_bf16 v[10:13], v[166:169], v[216:219], v[10:13]
	v_mfma_f32_16x16x32_bf16 v[62:65], v[162:165], v[196:199], v[62:65]
	v_mfma_f32_16x16x32_bf16 v[58:61], v[170:173], v[196:199], v[58:61]
	v_mfma_f32_16x16x32_bf16 v[46:49], v[162:165], v[204:207], v[46:49]
	v_mfma_f32_16x16x32_bf16 v[42:45], v[170:173], v[204:207], v[42:45]
	v_mfma_f32_16x16x32_bf16 v[30:33], v[162:165], v[212:215], v[30:33]
	v_mfma_f32_16x16x32_bf16 v[26:29], v[170:173], v[212:215], v[26:29]
	v_mfma_f32_16x16x32_bf16 v[14:17], v[162:165], v[220:223], v[14:17]
	v_mfma_f32_16x16x32_bf16 v[10:13], v[170:173], v[220:223], v[10:13]
	s_setprio 0
	s_setprio 1
	v_mfma_f32_16x16x32_bf16 v[54:57], v[176:179], v[192:195], v[54:57]
	v_mfma_f32_16x16x32_bf16 v[50:53], v[184:187], v[192:195], v[50:53]
	v_mfma_f32_16x16x32_bf16 v[38:41], v[176:179], v[200:203], v[38:41]
	v_mfma_f32_16x16x32_bf16 v[34:37], v[184:187], v[200:203], v[34:37]
	v_mfma_f32_16x16x32_bf16 v[22:25], v[176:179], v[208:211], v[22:25]
	v_mfma_f32_16x16x32_bf16 v[18:21], v[184:187], v[208:211], v[18:21]
	v_mfma_f32_16x16x32_bf16 v[6:9], v[176:179], v[216:219], v[6:9]
	v_mfma_f32_16x16x32_bf16 v[2:5], v[184:187], v[216:219], v[2:5]
	v_mfma_f32_16x16x32_bf16 v[54:57], v[180:183], v[196:199], v[54:57]
	v_mfma_f32_16x16x32_bf16 v[50:53], v[188:191], v[196:199], v[50:53]
	v_mfma_f32_16x16x32_bf16 v[38:41], v[180:183], v[204:207], v[38:41]
	v_mfma_f32_16x16x32_bf16 v[34:37], v[188:191], v[204:207], v[34:37]
	v_mfma_f32_16x16x32_bf16 v[22:25], v[180:183], v[212:215], v[22:25]
	v_mfma_f32_16x16x32_bf16 v[18:21], v[188:191], v[212:215], v[18:21]
	v_mfma_f32_16x16x32_bf16 v[6:9], v[180:183], v[220:223], v[6:9]
	v_mfma_f32_16x16x32_bf16 v[2:5], v[188:191], v[220:223], v[2:5]
	s_setprio 0
	s_barrier
	s_add_i32 s36, s54, 2
	s_add_u32 s34, s34, 0x100
	s_addc_u32 s35, s35, 0
	s_add_u32 s52, s52, 0x100
	s_addc_u32 s53, s53, 0
	s_cmp_ge_u32 s54, s51
	s_mov_b32 s54, s36
	s_cbranch_scc0 .LBB0_1545
	s_and_b64 vcc, exec, s[4:5]
	s_cbranch_vccz .LBB0_1548
	s_barrier
